# v9 plus PV blocks read V fragments two k-steps ahead (third fragment register set), same interleaved MFMA/read shape
# baseline (speedup 1.0000x reference)
; #define ATT_WAITBAR(N) asm volatile("s_waitcnt vmcnt(" #N ") lgkmcnt(0)\n\ts_barrier" ::: "memory")
; #define ATT_PV(slot) do { bf16x8 va[4], vb[4]; ATT_LDV(va, slot, 0); ATT_SB; ATT_LDV(vb, slot, 1); ATT_SB; ATT_MMV(va, 0); ATT_SB; ATT_LDV(va, slot, 2); ATT_SB; ATT_MMV(vb, 1); ATT_SB; \
;         ATT_LDV(vb, slot, 3); ATT_SB; ATT_MMV(va, 2); ATT_SB; ATT_MMV(vb, 3); ATT_SB; } while (0)
; template <bool NOSHIFT> __device__ __forceinline__ void diff_attn_unit(LAS unsigned char* lds, bf16_t* proj, const bf16_t* VT, int b, int h, int qb, const AttnConsts ac, const float* gsub, const int tid, bf16_t* obuf, int opitch, int ocol) {
;     ...
;     ATT_ISSUE(0); ATT_ISSUE(1);
;     ATT_WAITBAR(4);
;     for (int t = 0; t < NT; ++t) {
;         const int bo = (t & 3) * 16384, sl_cur = bo, sl_prev = ((t - 1) & 3) * 16384;
;         if (t + 2 < NT) ATT_ISSUE(t + 2);
;         const int kv0 = 64 * t;
;         if (c == 1 && t >= 1 && kv0 - 64 <= qmax) ATT_PV(sl_prev);
.LBB1_287:
.LBB1_288:
	s_cmp_gt_u32 s47, s83
	s_cselect_b64 s[80:81], -1, 0
	s_or_b64 s[80:81], s[76:77], s[80:81]
	s_and_b64 vcc, exec, s[80:81]
	s_cbranch_vccnz .LBB1_290
	s_add_i32 s15, s14, 0x10000
	s_and_b32 s15, s15, 0xc000
	v_add_u32_e32 v7, s15, v193
	ds_read_b128 v[8:11], v7
	ds_read_b128 v[12:15], v7 offset:4096
	ds_read_b128 v[112:115], v7 offset:8192
	ds_read_b128 v[116:119], v7 offset:12288
	v_add_u32_e32 v7, s15, v204
	ds_read_b128 v[120:123], v7
	ds_read_b128 v[124:127], v7 offset:4096
	ds_read_b128 v[128:131], v7 offset:8192
	ds_read_b128 v[132:135], v7 offset:12288
	v_add_u32_e32 v7, s15, v205
	ds_read_b128 v[208:211], v7
	ds_read_b128 v[212:215], v7 offset:4096
	ds_read_b128 v[216:219], v7 offset:8192
	ds_read_b128 v[220:223], v7 offset:12288
	s_setprio 1
	s_waitcnt lgkmcnt(11)
	v_mfma_f32_32x32x16_bf16 v[80:95], v[8:11], v[104:107], v[80:95]
	s_waitcnt lgkmcnt(10)
	v_mfma_f32_32x32x16_bf16 v[64:79], v[12:15], v[104:107], v[64:79]
	s_waitcnt lgkmcnt(9)
	v_mfma_f32_32x32x16_bf16 v[48:63], v[112:115], v[104:107], v[48:63]
	s_waitcnt lgkmcnt(8)
	v_mfma_f32_32x32x16_bf16 v[32:47], v[116:119], v[104:107], v[32:47]
	s_setprio 0
	v_add_u32_e32 v7, s15, v206
	ds_read_b128 v[8:11], v7
	ds_read_b128 v[12:15], v7 offset:4096
	ds_read_b128 v[112:115], v7 offset:8192
	ds_read_b128 v[116:119], v7 offset:12288
	s_setprio 1
	s_waitcnt lgkmcnt(11)
	v_mfma_f32_32x32x16_bf16 v[80:95], v[120:123], v[100:103], v[80:95]
	s_waitcnt lgkmcnt(10)
	v_mfma_f32_32x32x16_bf16 v[64:79], v[124:127], v[100:103], v[64:79]
	s_waitcnt lgkmcnt(9)
	v_mfma_f32_32x32x16_bf16 v[48:63], v[128:131], v[100:103], v[48:63]
	s_waitcnt lgkmcnt(8)
	v_mfma_f32_32x32x16_bf16 v[32:47], v[132:135], v[100:103], v[32:47]
	s_setprio 0
	s_setprio 1
	s_waitcnt lgkmcnt(7)
	v_mfma_f32_32x32x16_bf16 v[80:95], v[208:211], v[96:99], v[80:95]
	s_waitcnt lgkmcnt(6)
	v_mfma_f32_32x32x16_bf16 v[64:79], v[212:215], v[96:99], v[64:79]
	s_waitcnt lgkmcnt(5)
	v_mfma_f32_32x32x16_bf16 v[48:63], v[216:219], v[96:99], v[48:63]
	s_waitcnt lgkmcnt(4)
	v_mfma_f32_32x32x16_bf16 v[32:47], v[220:223], v[96:99], v[32:47]
	s_setprio 0
	s_setprio 1
	s_waitcnt lgkmcnt(3)
	v_mfma_f32_32x32x16_bf16 v[80:95], v[8:11], v[108:111], v[80:95]
	s_waitcnt lgkmcnt(2)
	v_mfma_f32_32x32x16_bf16 v[64:79], v[12:15], v[108:111], v[64:79]
	s_waitcnt lgkmcnt(1)
	v_mfma_f32_32x32x16_bf16 v[48:63], v[112:115], v[108:111], v[48:63]
	s_waitcnt lgkmcnt(0)
	v_mfma_f32_32x32x16_bf16 v[32:47], v[116:119], v[108:111], v[32:47]
	s_setprio 0

; __device__ __forceinline__ unsigned pk2(float lo, float hi) { f32x2 v = {lo, hi}; bf16x2_t b = __builtin_convertvector(v, bf16x2_t); return __builtin_bit_cast(unsigned, b); }
; #define ATT_PV(slot) do { bf16x8 va[4], vb[4]; ATT_LDV(va, slot, 0); ATT_SB; ATT_LDV(vb, slot, 1); ATT_SB; ATT_MMV(va, 0); ATT_SB; ATT_LDV(va, slot, 2); ATT_SB; ATT_MMV(vb, 1); ATT_SB; \
;         ATT_LDV(vb, slot, 3); ATT_SB; ATT_MMV(va, 2); ATT_SB; ATT_MMV(vb, 3); ATT_SB; } while (0)
; template <bool NOSHIFT> __device__ __forceinline__ void diff_attn_unit(LAS unsigned char* lds, bf16_t* proj, const bf16_t* VT, int b, int h, int qb, const AttnConsts ac, const float* gsub, const int tid, bf16_t* obuf, int opitch, int ocol) {
;     ...
;             for (int kk = 0; kk < 4; ++kk) { const int mt = kk >> 1, r0 = 8 * (kk & 1); u32x4 w;
;                 w.x = pk2(p[mt][r0], p[mt][r0 + 1]); w.y = pk2(p[mt][r0 + 2], p[mt][r0 + 3]); w.z = pk2(p[mt][r0 + 4], p[mt][r0 + 5]); w.w = pk2(p[mt][r0 + 6], p[mt][r0 + 7]);
;                 pf[kk] = __builtin_bit_cast(bf16x8, w); }
;             if (c == 0) ATT_PV(sl_cur);
.Latt_cvt_done:
	s_andn2_b64 vcc, exec, s[72:73]
	s_cbranch_vccnz .LBB1_298
	v_add_u32_e32 v116, s15, v193
	ds_read_b128 v[8:11], v116
	ds_read_b128 v[12:15], v116 offset:4096
	ds_read_b128 v[112:115], v116 offset:8192
	ds_read_b128 v[116:119], v116 offset:12288
	v_add_u32_e32 v132, s15, v204
	ds_read_b128 v[120:123], v132
	ds_read_b128 v[124:127], v132 offset:4096
	ds_read_b128 v[128:131], v132 offset:8192
	ds_read_b128 v[132:135], v132 offset:12288
	v_add_u32_e32 v224, s15, v205
	ds_read_b128 v[208:211], v224
	ds_read_b128 v[212:215], v224 offset:4096
	ds_read_b128 v[216:219], v224 offset:8192
	ds_read_b128 v[220:223], v224 offset:12288
	s_setprio 1
	s_waitcnt lgkmcnt(11)
	v_mfma_f32_32x32x16_bf16 v[80:95], v[8:11], v[104:107], v[80:95]
	s_waitcnt lgkmcnt(10)
	v_mfma_f32_32x32x16_bf16 v[64:79], v[12:15], v[104:107], v[64:79]
	s_waitcnt lgkmcnt(9)
	v_mfma_f32_32x32x16_bf16 v[48:63], v[112:115], v[104:107], v[48:63]
	s_waitcnt lgkmcnt(8)
	v_mfma_f32_32x32x16_bf16 v[32:47], v[116:119], v[104:107], v[32:47]
	s_setprio 0
	v_add_u32_e32 v224, s15, v206
	ds_read_b128 v[8:11], v224
	ds_read_b128 v[12:15], v224 offset:4096
	ds_read_b128 v[112:115], v224 offset:8192
	ds_read_b128 v[116:119], v224 offset:12288
	s_setprio 1
	s_waitcnt lgkmcnt(11)
	v_mfma_f32_32x32x16_bf16 v[80:95], v[120:123], v[100:103], v[80:95]
	s_waitcnt lgkmcnt(10)
	v_mfma_f32_32x32x16_bf16 v[64:79], v[124:127], v[100:103], v[64:79]
	s_waitcnt lgkmcnt(9)
	v_mfma_f32_32x32x16_bf16 v[48:63], v[128:131], v[100:103], v[48:63]
	s_waitcnt lgkmcnt(8)
	v_mfma_f32_32x32x16_bf16 v[32:47], v[132:135], v[100:103], v[32:47]
	s_setprio 0
	s_setprio 1
	s_waitcnt lgkmcnt(7)
	v_mfma_f32_32x32x16_bf16 v[80:95], v[208:211], v[96:99], v[80:95]
	s_waitcnt lgkmcnt(6)
	v_mfma_f32_32x32x16_bf16 v[64:79], v[212:215], v[96:99], v[64:79]
	s_waitcnt lgkmcnt(5)
	v_mfma_f32_32x32x16_bf16 v[48:63], v[216:219], v[96:99], v[48:63]
	s_waitcnt lgkmcnt(4)
	v_mfma_f32_32x32x16_bf16 v[32:47], v[220:223], v[96:99], v[32:47]
	s_setprio 0
	s_setprio 1
	s_waitcnt lgkmcnt(3)
	v_mfma_f32_32x32x16_bf16 v[80:95], v[8:11], v[108:111], v[80:95]
	s_waitcnt lgkmcnt(2)
	v_mfma_f32_32x32x16_bf16 v[64:79], v[12:15], v[108:111], v[64:79]
	s_waitcnt lgkmcnt(1)
	v_mfma_f32_32x32x16_bf16 v[48:63], v[112:115], v[108:111], v[48:63]
	s_waitcnt lgkmcnt(0)
	v_mfma_f32_32x32x16_bf16 v[32:47], v[116:119], v[108:111], v[32:47]
	s_setprio 0
	s_branch .LBB1_298
